# differential attention: work-queue pop of the next unit issued at the start of the current unit's epilogue
# baseline (speedup 1.0000x reference)
.LBB0_254:
	s_and_b64 vcc, exec, s[8:9]
	s_cbranch_vccz .LBB0_354
	v_readlane_b32 s24, v255, 28
	v_readlane_b32 s8, v251, 0
	s_lshr_b32 s0, s24, 1
	v_readlane_b32 s9, v251, 1
	v_readlane_b32 s10, v251, 2
	v_readlane_b32 s11, v251, 3
	v_readlane_b32 s12, v251, 4
	v_readlane_b32 s13, v251, 5
	v_readlane_b32 s14, v251, 6
	v_readlane_b32 s15, v251, 7
	v_readlane_b32 s16, v251, 8
	v_readlane_b32 s17, v251, 9
	s_cmp_eq_u32 s24, 0
	v_readlane_b32 s18, v251, 10
	v_readlane_b32 s19, v251, 11
	v_readlane_b32 s20, v251, 12
	v_readlane_b32 s21, v251, 13
	s_mov_b64 s[8:9], s[12:13]
	s_cselect_b64 vcc, -1, 0
	s_lshl_b64 s[4:5], s[0:1], 10
	s_mov_b64 s[10:11], s[14:15]
	v_mov_b32_e32 v0, 0x3ef1014c
	s_waitcnt lgkmcnt(0)
	v_mov_b32_e32 v1, 0x3e4ccccd
	s_add_u32 s8, s10, s4
	v_cndmask_b32_e32 v0, v0, v1, vcc
	s_addc_u32 s9, s11, s5
	v_lshlrev_b32_e32 v1, 2, v157
	global_load_dword v2, v1, s[8:9]
	global_load_dword v3, v1, s[8:9] offset:256
	v_mbcnt_lo_u32_b32 v5, -1, 0
	v_mbcnt_hi_u32_b32 v5, -1, v5
	s_mov_b32 s3, 0x3fb8aa3b
	v_lshlrev_b32_e32 v5, 2, v5
	v_xor_b32_e32 v5, 4, v5
	s_mov_b32 s4, 0xc2ce8ed0
	s_mov_b32 s5, 0x42b17218
	v_mov_b32_e32 v6, 0x7f800000
	s_mov_b64 s[12:13], s[16:17]
	s_mov_b64 s[14:15], s[18:19]
	s_mov_b64 s[16:17], s[20:21]
	v_readlane_b32 s44, v252, 36
	v_readlane_b32 s10, v252, 34
	v_readlane_b32 s11, v252, 35
	v_and_b32_e32 v148, 31, v138
	v_sub_f32_e32 v151, 1.0, v0
	v_lshlrev_b32_e32 v164, 7, v148
	v_readlane_b32 s43, v252, 50
	v_readlane_b32 s45, v252, 53
	v_readlane_b32 s46, v252, 55
	v_readlane_b32 s47, v252, 38
	v_readlane_b32 s48, v252, 39
	v_readlane_b32 s49, v252, 40
	v_readlane_b32 s50, v252, 42
	v_readlane_b32 s51, v252, 41
	v_readlane_b32 s77, v252, 43
	v_readlane_b32 s78, v252, 49
	v_readlane_b32 s25, v255, 29
	v_readlane_b32 s22, v251, 14
	v_readlane_b32 s23, v251, 15
	s_waitcnt vmcnt(0)
	v_mul_f32_e32 v4, v2, v3
	ds_bpermute_b32 v4, v5, v4
	s_waitcnt lgkmcnt(0)
	v_fmac_f32_e32 v4, v2, v3
	v_mbcnt_lo_u32_b32 v2, -1, 0
	v_mbcnt_hi_u32_b32 v2, -1, v2
	v_mbcnt_lo_u32_b32 v3, -1, 0
	v_mbcnt_hi_u32_b32 v3, -1, v3
	s_nop 0
	v_lshlrev_b32_e32 v2, 2, v2
	v_xor_b32_e32 v2, 8, v2
	ds_bpermute_b32 v2, v2, v4
	v_lshlrev_b32_e32 v3, 2, v3
	v_xor_b32_e32 v3, 16, v3
	s_waitcnt lgkmcnt(0)
	v_add_f32_e32 v2, v4, v2
	ds_bpermute_b32 v3, v3, v2
	s_waitcnt lgkmcnt(0)
	v_add_f32_e32 v2, v2, v3
	v_mbcnt_lo_u32_b32 v3, -1, 0
	v_mbcnt_hi_u32_b32 v3, -1, v3
	s_nop 0
	v_lshlrev_b32_e32 v3, 2, v3
	v_xor_b32_e32 v3, 32, v3
	ds_bpermute_b32 v3, v3, v2
	s_waitcnt lgkmcnt(0)
	v_add_f32_e32 v2, v2, v3
	v_mbcnt_lo_u32_b32 v3, -1, 0
	v_mbcnt_hi_u32_b32 v3, -1, v3
	s_nop 0
	v_lshlrev_b32_e32 v3, 2, v3
	v_xor_b32_e32 v3, 64, v3
	ds_bpermute_b32 v3, v3, v2
	s_waitcnt lgkmcnt(0)
	v_add_f32_e32 v2, v2, v3
	v_mbcnt_lo_u32_b32 v3, -1, 0
	v_mbcnt_hi_u32_b32 v3, -1, v3
	s_nop 0
	v_lshlrev_b32_e32 v3, 2, v3
	v_xor_b32_e32 v3, 0x80, v3
	ds_bpermute_b32 v3, v3, v2
	s_waitcnt lgkmcnt(0)
	v_add_f32_e32 v2, v2, v3
	v_mul_f32_e32 v3, 0x3fb8aa3b, v2
	v_fma_f32 v4, v2, s3, -v3
	v_rndne_f32_e32 v5, v3
	v_fmac_f32_e32 v4, 0x32a5705f, v2
	v_sub_f32_e32 v3, v3, v5
	v_add_f32_e32 v3, v3, v4
	v_exp_f32_e32 v3, v3
	v_cvt_i32_f32_e32 v4, v5
	v_cmp_ngt_f32_e32 vcc, s4, v2
	v_ldexp_f32 v3, v3, v4
	s_nop 0
	v_cndmask_b32_e32 v3, 0, v3, vcc
	v_cmp_nlt_f32_e32 vcc, s5, v2
	s_nop 1
	v_cndmask_b32_e32 v2, v6, v3, vcc
	global_load_dword v3, v1, s[8:9] offset:512
	s_nop 0
	global_load_dword v1, v1, s[8:9] offset:768
	v_mbcnt_lo_u32_b32 v5, -1, 0
	v_mbcnt_hi_u32_b32 v5, -1, v5
	v_cmp_eq_u32_e64 s[8:9], 0, v138
	v_lshlrev_b32_e32 v5, 2, v5
	v_xor_b32_e32 v5, 4, v5
	s_waitcnt vmcnt(0)
	v_mul_f32_e32 v4, v3, v1
	ds_bpermute_b32 v4, v5, v4
	s_waitcnt lgkmcnt(0)
	v_fmac_f32_e32 v4, v3, v1
	v_mbcnt_lo_u32_b32 v1, -1, 0
	v_mbcnt_hi_u32_b32 v1, -1, v1
	v_mbcnt_lo_u32_b32 v3, -1, 0
	v_mbcnt_hi_u32_b32 v3, -1, v3
	s_nop 0
	v_lshlrev_b32_e32 v1, 2, v1
	v_xor_b32_e32 v1, 8, v1
	ds_bpermute_b32 v1, v1, v4
	v_lshlrev_b32_e32 v3, 2, v3
	v_xor_b32_e32 v3, 16, v3
	s_waitcnt lgkmcnt(0)
	v_add_f32_e32 v1, v4, v1
	ds_bpermute_b32 v3, v3, v1
	s_waitcnt lgkmcnt(0)
	v_add_f32_e32 v1, v1, v3
	v_mbcnt_lo_u32_b32 v3, -1, 0
	v_mbcnt_hi_u32_b32 v3, -1, v3
	s_nop 0
	v_lshlrev_b32_e32 v3, 2, v3
	v_xor_b32_e32 v3, 32, v3
	ds_bpermute_b32 v3, v3, v1
	s_waitcnt lgkmcnt(0)
	v_add_f32_e32 v1, v1, v3
	v_mbcnt_lo_u32_b32 v3, -1, 0
	v_mbcnt_hi_u32_b32 v3, -1, v3
	s_nop 0
	v_lshlrev_b32_e32 v3, 2, v3
	v_xor_b32_e32 v3, 64, v3
	ds_bpermute_b32 v3, v3, v1
	s_waitcnt lgkmcnt(0)
	v_add_f32_e32 v1, v1, v3
	v_mbcnt_lo_u32_b32 v3, -1, 0
	v_mbcnt_hi_u32_b32 v3, -1, v3
	s_nop 0
	v_lshlrev_b32_e32 v3, 2, v3
	v_xor_b32_e32 v3, 0x80, v3
	ds_bpermute_b32 v3, v3, v1
	s_waitcnt lgkmcnt(0)
	v_add_f32_e32 v1, v1, v3
	v_mul_f32_e32 v3, 0x3fb8aa3b, v1
	v_fma_f32 v4, v1, s3, -v3
	v_rndne_f32_e32 v5, v3
	v_fmac_f32_e32 v4, 0x32a5705f, v1
	v_sub_f32_e32 v3, v3, v5
	v_add_f32_e32 v3, v3, v4
	v_exp_f32_e32 v3, v3
	v_cvt_i32_f32_e32 v4, v5
	v_cmp_ngt_f32_e32 vcc, s4, v1
	v_readlane_b32 s3, v251, 50
	v_lshrrev_b32_e32 v5, 2, v138
	v_ldexp_f32 v3, v3, v4
	v_cndmask_b32_e32 v3, 0, v3, vcc
	v_cmp_nlt_f32_e32 vcc, s5, v1
	s_lshl_b64 s[4:5], s[0:1], 9
	s_add_u32 s14, s12, s4
	s_addc_u32 s15, s13, s5
	s_lshl_b32 s0, s24, 8
	s_lshl_b64 s[4:5], s[0:1], 2
	s_add_u32 s4, s3, s4
	v_readlane_b32 s3, v251, 51
	s_addc_u32 s5, s3, s5
	s_lshl_b32 s3, s24, 2
	s_add_i32 s6, s3, s44
	s_lshl_b32 s6, s6, 6
	v_cndmask_b32_e32 v1, v6, v3, vcc
	s_ashr_i32 s7, s6, 31
	v_sub_f32_e32 v1, v2, v1
	v_lshlrev_b32_e32 v2, 3, v157
	s_lshl_b64 s[6:7], s[6:7], 2
	v_and_b32_e32 v150, 24, v2
	v_lshrrev_b32_e32 v2, 3, v157
	s_add_u32 s16, s10, s6
	v_readlane_b32 s6, v252, 37
	v_xor_b32_e32 v4, v2, v157
	s_addc_u32 s17, s11, s7
	s_add_i32 s3, s3, s6
	v_lshrrev_b32_e32 v3, 5, v157
	v_lshlrev_b32_e32 v4, 3, v4
	s_lshl_b32 s6, s3, 6
	v_and_b32_e32 v152, 56, v4
	v_lshlrev_b32_e32 v4, 2, v3
	s_ashr_i32 s7, s6, 31
	v_add_f32_e32 v149, v0, v1
	v_lshlrev_b32_e32 v0, 3, v3
	v_lshrrev_b32_e32 v1, 2, v157
	v_sub_u32_e32 v153, v148, v4
	v_and_or_b32 v4, v5, 3, v4
	v_lshlrev_b32_e32 v5, 1, v157
	v_bitop3_b32 v3, v3, v138, 7 bitop3:0x78
	s_lshl_b64 s[6:7], s[6:7], 2
	v_readlane_b32 s3, v252, 16
	v_lshlrev_b32_e32 v4, 6, v4
	v_and_b32_e32 v5, 32, v5
	v_lshlrev_b32_e32 v163, 4, v3
	s_add_u32 s18, s10, s6
	v_or_b32_e32 v168, s3, v1
	v_readlane_b32 s3, v252, 18
	v_or3_b32 v162, v5, v4, v150
	v_xor_b32_e32 v165, 32, v163
	v_xor_b32_e32 v166, 64, v163
	v_xor_b32_e32 v167, 0x60, v163
	s_addc_u32 s19, s11, s7
	v_or_b32_e32 v169, s3, v2
	v_lshlrev_b32_e32 v154, 1, v0
	v_cmp_gt_u32_e32 vcc, 0x80, v138
	s_and_saveexec_b64 s[10:11], vcc
	v_lshlrev_b32_e32 v0, 2, v138
	global_load_dword v1, v0, s[14:15]
	v_add_u32_e32 v0, 0x20340, v0
	s_waitcnt vmcnt(0)
	ds_write_b32 v0, v1
	s_waitcnt lgkmcnt(0)
	s_or_b64 exec, exec, s[10:11]
	s_and_saveexec_b64 s[10:11], s[8:9]
	global_atomic_add v203, v231, v214, s[16:17] sc0
	s_or_b64 exec, exec, s[10:11]
	s_branch .LBB0_258

.LBB0_258:
	s_barrier
	s_and_saveexec_b64 s[10:11], s[8:9]
	s_cbranch_execz .LBB0_266
	s_waitcnt vmcnt(0)
	v_mov_b32_e32 v0, v203
	s_movk_i32 s3, 0x7f
	v_cmp_lt_u32_e32 vcc, s3, v0
	s_and_saveexec_b64 s[12:13], vcc
	s_cbranch_execz .LBB0_265
	s_mov_b64 s[22:23], exec
	v_mbcnt_lo_u32_b32 v0, s22, 0
	v_mbcnt_hi_u32_b32 v0, s23, v0
	v_cmp_eq_u32_e32 vcc, 0, v0
	s_and_saveexec_b64 s[20:21], vcc
	s_cbranch_execz .LBB0_264
	s_bcnt1_i32_b64 s3, s[22:23]
	v_mov_b32_e32 v1, s3
	global_atomic_add v1, v231, v1, s[18:19] sc0

.LBB0_350:
	s_setprio 0
	s_and_saveexec_b64 s[6:7], s[8:9]
	global_atomic_add v203, v231, v214, s[16:17] sc0
	s_or_b64 exec, exec, s[6:7]
	v_mbcnt_lo_u32_b32 v64, -1, 0
	v_mbcnt_hi_u32_b32 v64, -1, v64
	s_nop 0
	v_lshlrev_b32_e32 v64, 2, v64
	v_xor_b32_e32 v64, 0x80, v64
	ds_bpermute_b32 v64, v64, v112
	s_barrier
	s_waitcnt lgkmcnt(0)
	v_add_f32_e32 v64, v112, v64
	v_div_scale_f32 v65, s[6:7], v64, v64, 1.0
	v_rcp_f32_e32 v66, v65
	v_div_scale_f32 v67, vcc, 1.0, v64, 1.0
	v_readlane_b32 s6, v252, 62
	v_fma_f32 v68, -v65, v66, 1.0
	v_fmac_f32_e32 v66, v68, v66
	v_mul_f32_e32 v68, v67, v66
	v_fma_f32 v69, -v65, v68, v67
	v_fmac_f32_e32 v68, v69, v66
	v_fma_f32 v65, -v65, v68, v67
	v_div_fmas_f32 v65, v65, v66, v68
	v_div_fixup_f32 v66, v65, v64, 1.0
	v_mov_b32_e32 v64, v157
	v_readlane_b32 s7, v252, 63
	v_and_b32_e32 v94, 31, v64
	v_ashrrev_i32_e32 v67, 5, v64
	v_or_b32_e32 v64, s47, v94
	v_mul_u32_u24_e32 v64, 0x204, v64
	v_lshlrev_b32_e32 v65, 4, v67
	v_add3_u32 v95, 0, v64, v65
	s_and_b64 vcc, exec, s[6:7]
	s_cbranch_vccz .LBB0_352
	v_mul_f32_e32 v64, v149, v66
	v_pk_mul_f32 v[68:69], v[0:1], v[64:65] op_sel_hi:[1,0]
	ds_write2_b32 v95, v68, v69 offset1:1
	v_pk_mul_f32 v[68:69], v[2:3], v[64:65] op_sel_hi:[1,0]
	ds_write2_b32 v95, v68, v69 offset0:2 offset1:3
	v_pk_mul_f32 v[68:69], v[4:5], v[64:65] op_sel_hi:[1,0]
	ds_write2_b32 v95, v68, v69 offset0:8 offset1:9
	v_pk_mul_f32 v[68:69], v[6:7], v[64:65] op_sel_hi:[1,0]
	ds_write2_b32 v95, v68, v69 offset0:10 offset1:11
	v_pk_mul_f32 v[68:69], v[8:9], v[64:65] op_sel_hi:[1,0]
	ds_write2_b32 v95, v68, v69 offset0:16 offset1:17
	v_pk_mul_f32 v[68:69], v[10:11], v[64:65] op_sel_hi:[1,0]
	ds_write2_b32 v95, v68, v69 offset0:18 offset1:19
	v_pk_mul_f32 v[68:69], v[12:13], v[64:65] op_sel_hi:[1,0]
	ds_write2_b32 v95, v68, v69 offset0:24 offset1:25
	v_pk_mul_f32 v[68:69], v[14:15], v[64:65] op_sel_hi:[1,0]
	ds_write2_b32 v95, v68, v69 offset0:26 offset1:27
	v_pk_mul_f32 v[68:69], v[16:17], v[64:65] op_sel_hi:[1,0]
	ds_write2_b32 v95, v68, v69 offset0:32 offset1:33
	v_pk_mul_f32 v[68:69], v[18:19], v[64:65] op_sel_hi:[1,0]
	ds_write2_b32 v95, v68, v69 offset0:34 offset1:35
	v_pk_mul_f32 v[68:69], v[20:21], v[64:65] op_sel_hi:[1,0]
	ds_write2_b32 v95, v68, v69 offset0:40 offset1:41
	v_pk_mul_f32 v[68:69], v[22:23], v[64:65] op_sel_hi:[1,0]
	ds_write2_b32 v95, v68, v69 offset0:42 offset1:43
	v_pk_mul_f32 v[68:69], v[24:25], v[64:65] op_sel_hi:[1,0]
	ds_write2_b32 v95, v68, v69 offset0:48 offset1:49
	v_pk_mul_f32 v[68:69], v[26:27], v[64:65] op_sel_hi:[1,0]
	ds_write2_b32 v95, v68, v69 offset0:50 offset1:51
	v_pk_mul_f32 v[68:69], v[28:29], v[64:65] op_sel_hi:[1,0]
	ds_write2_b32 v95, v68, v69 offset0:56 offset1:57
	v_pk_mul_f32 v[68:69], v[30:31], v[64:65] op_sel_hi:[1,0]
	ds_write2_b32 v95, v68, v69 offset0:58 offset1:59
	v_pk_mul_f32 v[68:69], v[32:33], v[64:65] op_sel_hi:[1,0]
	ds_write2_b32 v95, v68, v69 offset0:64 offset1:65
	v_pk_mul_f32 v[68:69], v[34:35], v[64:65] op_sel_hi:[1,0]
	ds_write2_b32 v95, v68, v69 offset0:66 offset1:67
	v_pk_mul_f32 v[68:69], v[36:37], v[64:65] op_sel_hi:[1,0]
	ds_write2_b32 v95, v68, v69 offset0:72 offset1:73
	v_pk_mul_f32 v[68:69], v[38:39], v[64:65] op_sel_hi:[1,0]
	ds_write2_b32 v95, v68, v69 offset0:74 offset1:75
	v_pk_mul_f32 v[68:69], v[40:41], v[64:65] op_sel_hi:[1,0]
	ds_write2_b32 v95, v68, v69 offset0:80 offset1:81
	v_pk_mul_f32 v[68:69], v[42:43], v[64:65] op_sel_hi:[1,0]
	ds_write2_b32 v95, v68, v69 offset0:82 offset1:83
	v_pk_mul_f32 v[68:69], v[44:45], v[64:65] op_sel_hi:[1,0]
	ds_write2_b32 v95, v68, v69 offset0:88 offset1:89
	v_pk_mul_f32 v[68:69], v[46:47], v[64:65] op_sel_hi:[1,0]
	ds_write2_b32 v95, v68, v69 offset0:90 offset1:91
	v_pk_mul_f32 v[68:69], v[48:49], v[64:65] op_sel_hi:[1,0]
	ds_write2_b32 v95, v68, v69 offset0:96 offset1:97
	v_pk_mul_f32 v[68:69], v[50:51], v[64:65] op_sel_hi:[1,0]
	ds_write2_b32 v95, v68, v69 offset0:98 offset1:99
	v_pk_mul_f32 v[68:69], v[52:53], v[64:65] op_sel_hi:[1,0]
	ds_write2_b32 v95, v68, v69 offset0:104 offset1:105
	v_pk_mul_f32 v[68:69], v[54:55], v[64:65] op_sel_hi:[1,0]
	ds_write2_b32 v95, v68, v69 offset0:106 offset1:107
	v_pk_mul_f32 v[68:69], v[56:57], v[64:65] op_sel_hi:[1,0]
	ds_write2_b32 v95, v68, v69 offset0:112 offset1:113
	v_pk_mul_f32 v[68:69], v[58:59], v[64:65] op_sel_hi:[1,0]
	ds_write2_b32 v95, v68, v69 offset0:114 offset1:115
	v_pk_mul_f32 v[68:69], v[60:61], v[64:65] op_sel_hi:[1,0]
	v_pk_mul_f32 v[64:65], v[62:63], v[64:65] op_sel_hi:[1,0]
	ds_write2_b32 v95, v68, v69 offset0:120 offset1:121
	ds_write2_b32 v95, v64, v65 offset0:122 offset1:123
